# NSA phase: static s_setprio 1 for waves 4-7
# speedup vs baseline: 1.0007x; 1.0007x over previous
; #define LAS __attribute__((address_space(3)))
; __device__ __forceinline__ const float* P_in(const Params&, int i) { return (const float*)karg_ld(8 * i); }
; #define LAUNDER(x) asm volatile("" : "+v"(x))
; __device__ __forceinline__ void nsa_unit(const Params& p, int bg, int jq, LAS unsigned char* lds, int wave, int lane, bool build_lut) {
;     LAUNDER(lane);
;     const unsigned char* ws = P_ws(p);
;     const bf16_t* qb = (const bf16_t*)(ws + WS_R1 + R_Q);
;     const bf16_t* kcmp = (const bf16_t*)(ws + WS_R1 + R_KCMP) + (size_t)bg * NCMP * 64;
;     const bf16_t* vcmpT = (const bf16_t*)(ws + WS_R1 + R_VCMPT) + (size_t)bg * NCMP * 64;
;     const unsigned char* ks8 = ws + WS_R1 + R_KS + (size_t)bg * S * 64;
;     const unsigned char* vs8 = ws + WS_R1 + R_VST + (size_t)bg * S * 64;
;     const bf16_t* kwb = (const bf16_t*)(ws + WS_R1 + R_KW) + (size_t)bg * S * 64;
;     const bf16_t* vwT = (const bf16_t*)(ws + WS_R1 + R_VWT) + (size_t)bg * S * 64;
;     const float* gates = (const float*)(ws + WS_R1 + R_GATES);
;     bf16_t* mixed = (bf16_t*)(ws + WS_AN);
;     const float* relb = P_in(p, 1);
;     const int b = bg >> 1, g = bg & 1;
;     LAS float* imp = (LAS float*)(lds + wave * NSA_WAVE_LDS);
;     LAS unsigned* selw = (LAS unsigned*)(lds + wave * NSA_WAVE_LDS + 8192);
;     LAS float* lut = (LAS float*)(lds + wave * NSA_WAVE_LDS + 8192 + 256);
;     LAS int* list = (LAS int*)(lds + wave * NSA_WAVE_LDS + 8192 + 256 + 2112);
;     const int c = lane & 31, h = lane >> 5, ql = c >> 2, r = c & 3;
;     const int tq0 = 64 * jq + 8 * wave, tq = tq0 + ql;
;     const size_t tok = (size_t)b * S + tq;
;     if (build_lut) {
;         for (int e = lane; e < 4 * 129; e += 64) {
;             const int rr = e / 129, n = e % 129;
;             int bk = n;
;             if (n >= 16) bk = 16 + (n >= 19) + (n >= 21) + (n >= 24) + (n >= 27) + (n >= 31) + (n >= 35) + (n >= 40) + (n >= 46) + (n >= 52) + (n >= 59) + (n >= 67) + (n >= 77) + (n >= 87) + (n >= 99) + (n >= 113);
;             lut[rr * 132 + n] = relb[bk * 8 + g * 4 + rr] * LOG2E;
;         }
; __global__ void __launch_bounds__(NTHREADS, 2) fwd_megakernel(Params p) {
;     ...
;                     for (int i = 0; i < 4; ++i) {
;                         const int jq = (i >> 1) * 128 + ((i & 1) ? (127 - j) : j);
;                         nsa_unit(p, bg, jq, lds, WAVE_F, LANE_F, i == 0);
.LBB0_1046:
	v_mov_b32_e32 v1, v222
	s_movk_i32 s6, 0xa8
	v_readfirstlane_b32 s4, v1
	s_ashr_i32 s12, s4, 6
	s_cmp_lt_u32 s12, 4
	s_cbranch_scc1 .Lno_prio
	s_setprio 1

; #define LAS __attribute__((address_space(3)))
; __device__ __forceinline__ unsigned xb_add(unsigned* p, unsigned v) { return __hip_atomic_fetch_add(p, v, __ATOMIC_RELAXED, __HIP_MEMORY_SCOPE_AGENT); }
; __device__ __forceinline__ unsigned xb_xcc_id() { return (unsigned)__builtin_amdgcn_s_getreg((3 << 11) | 20) & 0xFu; }
; __device__ __forceinline__ void xcd_barrier(unsigned* bar, volatile LAS unsigned* st) {
;     asm volatile("s_waitcnt vmcnt(0)" ::: "memory");
;     __syncthreads();
;     if (threadIdx.x == 0) {
;         const unsigned x = xb_xcc_id();
;         __builtin_amdgcn_s_waitcnt(0);
;         unsigned nloc = st[0], nx = st[1];
;         if (nloc == 0u) { xcd_barrier_complete(bar, x, nloc, nx); st[0] = nloc; st[1] = nx; }
;         const unsigned old = xb_add(&bar[XB_XSUB(x)], 1u);
;         const unsigned gen = old / nloc;
.LBB0_1329:
	s_setprio 0
	s_movk_i32 s6, 0xa8
	s_waitcnt vmcnt(0)
	s_barrier
	s_mov_b64 s[4:5], exec
	v_readlane_b32 s8, v253, 62
	v_readlane_b32 s9, v253, 63
	s_and_b64 s[8:9], s[4:5], s[8:9]
	s_mov_b64 exec, s[8:9]
	s_cbranch_execz .LBB0_1381
	s_ashr_i32 s7, s6, 31
	s_add_u32 s6, s0, s6
	v_readlane_b32 s9, v253, 58
	s_addc_u32 s7, s1, s7
	s_load_dwordx2 s[6:7], s[6:7], 0x0
	v_mov_b32_e32 v1, s9
	s_getreg_b32 s8, hwreg(HW_REG_XCC_ID, 0, 4)
	s_waitcnt vmcnt(0) expcnt(0) lgkmcnt(0)
	ds_read_b32 v3, v1
	v_readlane_b32 s9, v253, 59
	s_and_b32 s22, s8, 15
	s_waitcnt lgkmcnt(0)
	v_cmp_ne_u32_e32 vcc, 0, v3
	v_mov_b32_e32 v1, s9
	ds_read_b32 v2, v1
	s_cbranch_vccnz .LBB0_1345
	s_add_u32 s8, s6, 0x1000
	s_addc_u32 s9, s7, 0
	s_add_u32 s10, s6, 0x1100
	s_addc_u32 s11, s7, 0
	s_add_u32 s12, s6, 0x1200
	s_addc_u32 s13, s7, 0
	s_add_u32 s14, s6, 0x1300
	s_addc_u32 s15, s7, 0
	s_mov_b32 s23, 1
	s_branch .LBB0_1333
